# Mamba gate: next item's three loads prefetched into registers (constant stride), vmcnt(1) instead of per-item full waits
# baseline (speedup 1.0000x reference)
.LBB0_2516:
	s_or_b64 exec, exec, s[0:1]
	s_waitcnt lgkmcnt(0)
	v_mov_b32_e32 v2, v0
	s_barrier
	v_readlane_b32 s0, v252, 57
	v_lshrrev_b32_e32 v12, 6, v2
	v_mov_b32_e32 v2, v0
	v_add_u32_e32 v11, s0, v12
	s_mov_b32 s0, 0x21000
	v_cmp_gt_i32_e32 vcc, s0, v11
	s_mov_b64 s[2:3], exec
	v_readlane_b32 s4, v253, 10
	v_readlane_b32 s5, v253, 11
	v_readlane_b32 s6, v253, 12
	v_readlane_b32 s7, v253, 13
	v_readlane_b32 s8, v253, 14
	v_readlane_b32 s9, v253, 15
	v_readlane_b32 s10, v253, 16
	v_readlane_b32 s11, v253, 17
	v_readlane_b32 s4, v252, 4
	s_and_b64 s[0:1], s[2:3], vcc
	v_readlane_b32 s12, v253, 18
	v_readlane_b32 s13, v253, 19
	v_readlane_b32 s6, v252, 6
	v_readlane_b32 s7, v252, 7
	v_readlane_b32 s8, v252, 8
	v_readlane_b32 s9, v252, 9
	v_readlane_b32 s14, v253, 20
	v_readlane_b32 s15, v253, 21
	v_readlane_b32 s16, v253, 22
	v_readlane_b32 s17, v253, 23
	v_readlane_b32 s18, v253, 24
	v_readlane_b32 s19, v253, 25
	v_readlane_b32 s5, v252, 5
	v_readlane_b32 s10, v252, 10
	v_readlane_b32 s11, v252, 11
	s_mov_b64 exec, s[0:1]
	s_cbranch_execz .LBB0_2519
	v_lshlrev_b32_e32 v2, 3, v2
	v_and_b32_e32 v10, 0x1f8, v2
	v_ashrrev_i32_e32 v2, 31, v11
	v_lshrrev_b32_e32 v2, 30, v2
	v_add_u32_e32 v2, v11, v2
	s_mov_b64 s[14:15], s[6:7]
	s_mov_b64 s[16:17], s[8:9]
	v_readlane_b32 s4, v252, 12
	v_and_b32_e32 v2, 0x7ffffc, v2
	v_readlane_b32 s5, v252, 13
	v_sub_u32_e32 v2, v11, v2
	s_mov_b64 s[0:1], s[4:5]
	v_lshlrev_b32_e32 v6, 9, v2
	v_mov_b32_e32 v4, s0
	v_mov_b32_e32 v5, s1
	v_ashrrev_i32_e32 v7, 31, v6
	v_mov_b32_e32 v3, 0
	v_lshl_add_u64 v[4:5], v[6:7], 2, v[4:5]
	v_lshlrev_b32_e32 v2, 2, v10
	v_lshl_add_u64 v[6:7], v[4:5], 0, v[2:3]
	global_load_dwordx4 v[2:5], v[6:7], off
	s_nop 0
	global_load_dwordx4 v[6:9], v[6:7], off offset:16
	v_readlane_b32 s6, v252, 14
	v_readlane_b32 s7, v252, 15
	v_readlane_b32 s8, v252, 16
	v_lshlrev_b32_e32 v12, 9, v12
	v_lshl_add_u32 v12, s96, 12, v12
	s_lshl_b32 s4, s60, 9
	s_mov_b64 s[6:7], 0
	v_mov_b32_e32 v13, 0x358637bd
	s_mov_b32 s5, 0xf800000
	v_mov_b32_e32 v14, 0x260
	s_mov_b32 s8, 0x20fff
	v_readlane_b32 s9, v252, 17
	v_readlane_b32 s10, v252, 18
	v_readlane_b32 s11, v252, 19
	v_ashrrev_i32_e32 v15, 31, v11
	v_lshrrev_b32_e32 v15, 30, v15
	v_add_u32_e32 v15, v11, v15
	v_ashrrev_i32_e32 v16, 2, v15
	v_lshlrev_b32_e32 v15, 11, v16
	v_ashrrev_i32_e32 v17, 31, v16
	v_sub_u32_e32 v18, v12, v15
	v_lshlrev_b64 v[16:17], 11, v[16:17]
	v_ashrrev_i32_e32 v19, 31, v18
	v_lshl_add_u64 v[16:17], v[16:17], 0, v[18:19]
	v_or_b32_e32 v16, v16, v10
	v_lshlrev_b64 v[28:29], 1, v[16:17]
	v_lshl_add_u64 v[24:25], v[16:17], 2, s[14:15]
	v_lshl_add_u64 v[20:21], s[12:13], 0, v[28:29]
	global_load_dwordx4 v[100:103], v[24:25], off
	global_load_dwordx4 v[104:107], v[20:21], off
	global_load_dwordx4 v[108:111], v[24:25], off offset:16
	s_mov_b64 s[98:99], 0x400000
	s_mov_b64 s[100:101], 0x200000
	s_waitcnt vmcnt(0)
.LBB0_2518:
	v_ashrrev_i32_e32 v15, 31, v11
	v_lshrrev_b32_e32 v15, 30, v15
	v_add_u32_e32 v15, v11, v15
	v_ashrrev_i32_e32 v16, 2, v15
	v_lshlrev_b32_e32 v15, 11, v16
	v_ashrrev_i32_e32 v17, 31, v16
	v_sub_u32_e32 v18, v12, v15
	v_lshlrev_b64 v[16:17], 11, v[16:17]
	v_ashrrev_i32_e32 v19, 31, v18
	v_lshl_add_u64 v[16:17], v[16:17], 0, v[18:19]
	v_or_b32_e32 v16, v16, v10
	v_lshlrev_b64 v[28:29], 1, v[16:17]
	v_lshl_add_u64 v[24:25], v[16:17], 2, s[14:15]
	v_lshl_add_u64 v[20:21], s[12:13], 0, v[28:29]
	v_lshl_add_u64 v[112:113], v[24:25], 0, s[98:99]
	v_lshl_add_u64 v[114:115], v[20:21], 0, s[100:101]
	s_waitcnt vmcnt(1)
	v_mov_b32_e32 v16, v100
	v_mov_b32_e32 v17, v101
	v_mov_b32_e32 v18, v102
	v_mov_b32_e32 v19, v103
	v_mov_b32_e32 v20, v104
	v_mov_b32_e32 v21, v105
	v_mov_b32_e32 v22, v106
	v_mov_b32_e32 v23, v107
	v_mov_b32_e32 v24, v108
	v_mov_b32_e32 v25, v109
	v_mov_b32_e32 v26, v110
	v_mov_b32_e32 v27, v111
	global_load_dwordx4 v[100:103], v[112:113], off
	global_load_dwordx4 v[104:107], v[114:115], off
	global_load_dwordx4 v[108:111], v[112:113], off offset:16
	v_add_u32_e32 v11, s60, v11
	v_cmp_lt_i32_e32 vcc, s8, v11
	s_or_b64 s[6:7], vcc, s[6:7]
	v_add_u32_e32 v12, s4, v12
	v_lshl_add_u64 v[28:29], s[16:17], 0, v[28:29]
	v_lshlrev_b32_e32 v15, 16, v20
	v_and_b32_e32 v20, 0xffff0000, v20
	v_lshlrev_b32_e32 v30, 16, v21
	v_and_b32_e32 v21, 0xffff0000, v21
	v_lshlrev_b32_e32 v31, 16, v22
	v_and_b32_e32 v22, 0xffff0000, v22
	v_lshlrev_b32_e32 v32, 16, v23
	v_and_b32_e32 v23, 0xffff0000, v23
	v_mul_f32_e32 v33, 0xbfb8aa3b, v15
	v_mul_f32_e32 v34, 0xbfb8aa3b, v20
	v_mul_f32_e32 v35, 0xbfb8aa3b, v30
	v_mul_f32_e32 v36, 0xbfb8aa3b, v21
	v_mul_f32_e32 v37, 0xbfb8aa3b, v31
	v_mul_f32_e32 v38, 0xbfb8aa3b, v22
	v_mul_f32_e32 v40, 0xbfb8aa3b, v23
	v_exp_f32_e32 v33, v33
	v_exp_f32_e32 v34, v34
	v_exp_f32_e32 v35, v35
	v_mul_f32_e32 v39, 0xbfb8aa3b, v32
	v_exp_f32_e32 v36, v36
	v_exp_f32_e32 v37, v37
	v_exp_f32_e32 v38, v38
	v_exp_f32_e32 v40, v40
	v_exp_f32_e32 v39, v39
	v_add_f32_e32 v33, 1.0, v33
	v_add_f32_e32 v34, 1.0, v34
	v_add_f32_e32 v35, 1.0, v35
	v_add_f32_e32 v36, 1.0, v36
	v_add_f32_e32 v37, 1.0, v37
	v_add_f32_e32 v38, 1.0, v38
	v_add_f32_e32 v40, 1.0, v40
	v_rcp_f32_e32 v33, v33
	v_rcp_f32_e32 v34, v34
	v_rcp_f32_e32 v35, v35
	v_add_f32_e32 v39, 1.0, v39
	v_rcp_f32_e32 v36, v36
	v_rcp_f32_e32 v37, v37
	v_rcp_f32_e32 v38, v38
	v_rcp_f32_e32 v40, v40
	v_rcp_f32_e32 v39, v39
	v_mul_f32_e32 v15, v33, v15
	v_mul_f32_e32 v20, v34, v20
	v_mul_f32_e32 v30, v35, v30
	v_mul_f32_e32 v21, v36, v21
	v_mul_f32_e32 v31, v37, v31
	v_mul_f32_e32 v22, v38, v22
	v_mul_f32_e32 v23, v40, v23
	v_mul_f32_e32 v15, v16, v15
	v_mul_f32_e32 v16, v17, v20
	v_mul_f32_e32 v17, v18, v30
	v_mul_f32_e32 v32, v39, v32
	v_mul_f32_e32 v18, v19, v21
	v_mul_f32_e32 v19, v24, v31
	v_mul_f32_e32 v20, v25, v22
	v_mul_f32_e32 v22, v27, v23
	v_mul_f32_e32 v23, v15, v15
	v_mul_f32_e32 v24, v17, v17
	v_mul_f32_e32 v21, v26, v32
	v_mul_f32_e32 v25, v19, v19
	v_fmac_f32_e32 v23, v16, v16
	v_fmac_f32_e32 v24, v18, v18
	v_mul_f32_e32 v26, v21, v21
	v_fmac_f32_e32 v25, v20, v20
	v_add_f32_e32 v23, v23, v24
	v_fmac_f32_e32 v26, v22, v22
	v_add_f32_e32 v23, v25, v23
	v_add_f32_e32 v23, v26, v23
	ds_bpermute_b32 v24, v1, v23
	s_waitcnt lgkmcnt(0)
	v_add_f32_e32 v23, v23, v24
	ds_bpermute_b32 v24, v234, v23
	s_waitcnt lgkmcnt(0)
	v_add_f32_e32 v23, v23, v24
	ds_bpermute_b32 v24, v235, v23
	s_waitcnt lgkmcnt(0)
	v_add_f32_e32 v23, v23, v24
	ds_bpermute_b32 v24, v236, v23
	s_waitcnt lgkmcnt(0)
	v_add_f32_e32 v23, v23, v24
	ds_bpermute_b32 v24, v237, v23
	s_waitcnt lgkmcnt(0)
	v_add_f32_e32 v23, v23, v24
	ds_bpermute_b32 v24, v238, v23
	s_waitcnt lgkmcnt(0)
	v_add_f32_e32 v23, v23, v24
	v_fmamk_f32 v23, v23, 0x3b000000, v13
	v_mul_f32_e32 v24, 0x4f800000, v23
	v_cmp_gt_f32_e32 vcc, s5, v23
	s_nop 1
	v_cndmask_b32_e32 v23, v23, v24, vcc
	v_sqrt_f32_e32 v24, v23
	s_nop 0
	v_add_u32_e32 v25, -1, v24
	v_add_u32_e32 v26, 1, v24
	v_fma_f32 v27, -v25, v24, v23
	v_fma_f32 v30, -v26, v24, v23
	v_cmp_ge_f32_e64 s[0:1], 0, v27
	s_nop 1
	v_cndmask_b32_e64 v24, v24, v25, s[0:1]
	v_cmp_lt_f32_e64 s[0:1], 0, v30
	s_nop 1
	v_cndmask_b32_e64 v24, v24, v26, s[0:1]
	v_mul_f32_e32 v25, 0x37800000, v24
	v_cndmask_b32_e32 v24, v24, v25, vcc
	v_cmp_class_f32_e32 vcc, v23, v14
	s_nop 1
	v_cndmask_b32_e32 v23, v24, v23, vcc
	v_div_scale_f32 v24, s[0:1], v23, v23, 1.0
	v_rcp_f32_e32 v26, v24
	v_div_scale_f32 v25, vcc, 1.0, v23, 1.0
	v_fma_f32 v27, -v24, v26, 1.0
	v_fmac_f32_e32 v26, v27, v26
	v_mul_f32_e32 v27, v25, v26
	v_fma_f32 v30, -v24, v27, v25
	v_fmac_f32_e32 v27, v30, v26
	v_fma_f32 v24, -v24, v27, v25
	v_div_fmas_f32 v24, v24, v26, v27
	v_div_fixup_f32 v23, v24, v23, 1.0
	v_mul_f32_e32 v16, v16, v23
	v_mul_f32_e32 v17, v17, v23
	v_mul_f32_e32 v18, v18, v23
	v_mul_f32_e32 v19, v19, v23
	v_mul_f32_e32 v15, v15, v23
	v_mul_f32_e32 v20, v20, v23
	v_mul_f32_e32 v21, v21, v23
	v_mul_f32_e32 v22, v22, v23
	v_mul_f32_e32 v16, v3, v16
	v_mul_f32_e32 v17, v4, v17
	v_mul_f32_e32 v18, v5, v18
	v_mul_f32_e32 v19, v6, v19
	v_mul_f32_e32 v15, v2, v15
	v_mul_f32_e32 v20, v7, v20
	v_mul_f32_e32 v21, v8, v21
	v_mul_f32_e32 v22, v9, v22
	v_cvt_pk_bf16_f32 v16, v15, v16
	v_cvt_pk_bf16_f32 v17, v17, v18
	v_cvt_pk_bf16_f32 v18, v19, v20
	v_cvt_pk_bf16_f32 v19, v21, v22
	global_store_dwordx4 v[28:29], v[16:19], off
	s_andn2_b64 exec, exec, s[6:7]
	s_cbranch_execnz .LBB0_2518
